# prompt indexer select_query: hand-written fast path (16-bit monotone keys, two-level histogram, exact ranking of at most 64 ties by 64-bit keys) in front of the compiled body, which stays as the fallb
# speedup vs baseline: 1.0014x; 1.0014x over previous
.LBB0_721:
	s_add_i32 s4, s28, s89
	s_cmpk_gt_i32 s4, 0xff
	s_cbranch_scc0 .Lsel_orig
	s_lshr_b32 s6, s4, 8
	s_and_b32 s7, s4, 0xff
	s_and_b32 s80, s28, 7
	s_add_i32 s0, s28, s13
	s_ashr_i32 s1, s0, 31
	s_lshl_b64 s[0:1], s[0:1], 13
	s_mov_b64 s[2:3], 0x1000
	s_nop 0
	v_lshl_add_u64 v[34:35], v[84:85], 0, s[0:1]
	v_lshl_add_u64 v[184:185], v[34:35], 0, s[2:3]
	global_load_dwordx4 v[2:5], v[34:35], off
	global_load_dwordx4 v[6:9], v[34:35], off offset:1024
	s_cmpk_lt_u32 s6, 2
	s_cbranch_scc1 .Lsel_ld_done
	global_load_dwordx4 v[10:13], v[34:35], off offset:2048
	s_cmpk_lt_u32 s6, 3
	s_cbranch_scc1 .Lsel_ld_done
	global_load_dwordx4 v[14:17], v[34:35], off offset:3072
	s_cmpk_lt_u32 s6, 4
	s_cbranch_scc1 .Lsel_ld_done
	global_load_dwordx4 v[18:21], v[184:185], off
	s_cmpk_lt_u32 s6, 5
	s_cbranch_scc1 .Lsel_ld_done
	global_load_dwordx4 v[22:25], v[184:185], off offset:1024
	s_cmpk_lt_u32 s6, 6
	s_cbranch_scc1 .Lsel_ld_done
	global_load_dwordx4 v[26:29], v[184:185], off offset:2048
	s_cmpk_lt_u32 s6, 7
	s_cbranch_scc1 .Lsel_ld_done
	global_load_dwordx4 v[30:33], v[184:185], off offset:3072
.Lsel_ld_done:
	v_lshlrev_b32_e32 v231, 2, v198
	s_lshl_b32 s0, s80, 10
	s_add_i32 s0, s0, 0xa000
	s_nop 1
	v_mov_b32_e32 v232, s0
	v_lshl_add_u32 v186, v198, 4, v232
	v_mov_b32_e32 v188, 0
	v_mov_b32_e32 v189, 0
	v_mov_b32_e32 v190, 0
	v_mov_b32_e32 v191, 0
	ds_write_b128 v186, v[188:191]
	s_lshl_b32 s1, s80, 8
	s_add_i32 s1, s1, 0xc000
	s_nop 1
	v_add_u32_e32 v237, s1, v231
	ds_write_b32 v237, v188
	v_mov_b32_e32 v233, 1
	v_add_u32_e32 v187, 1, v231
	v_add_u32_e32 v192, 2, v231
	v_add_u32_e32 v193, 3, v231
	v_cmp_le_u32_e64 s[72:73], v231, s7
	v_cmp_le_u32_e64 s[74:75], v187, s7
	v_cmp_le_u32_e64 s[76:77], v192, s7
	v_cmp_le_u32_e64 s[78:79], v193, s7
	s_waitcnt vmcnt(0)
	v_readfirstlane_b32 s0, v2
	s_nop 1
	v_mov_b32_e32 v194, s0
	s_cmpk_lg_u32 s6, 1
	s_cbranch_scc1 .Lsel_f1_1
	v_cndmask_b32_e64 v6, v194, v6, s[72:73]
	v_cndmask_b32_e64 v7, v194, v7, s[74:75]
	v_cndmask_b32_e64 v8, v194, v8, s[76:77]
	v_cndmask_b32_e64 v9, v194, v9, s[78:79]
	s_branch .Lsel_f1_done
.Lsel_f1_1:
	s_cmpk_lg_u32 s6, 2
	s_cbranch_scc1 .Lsel_f1_2
	v_cndmask_b32_e64 v10, v194, v10, s[72:73]
	v_cndmask_b32_e64 v11, v194, v11, s[74:75]
	v_cndmask_b32_e64 v12, v194, v12, s[76:77]
	v_cndmask_b32_e64 v13, v194, v13, s[78:79]
	s_branch .Lsel_f1_done
.Lsel_f1_2:
	s_cmpk_lg_u32 s6, 3
	s_cbranch_scc1 .Lsel_f1_3
	v_cndmask_b32_e64 v14, v194, v14, s[72:73]
	v_cndmask_b32_e64 v15, v194, v15, s[74:75]
	v_cndmask_b32_e64 v16, v194, v16, s[76:77]
	v_cndmask_b32_e64 v17, v194, v17, s[78:79]
	s_branch .Lsel_f1_done
.Lsel_f1_3:
	s_cmpk_lg_u32 s6, 4
	s_cbranch_scc1 .Lsel_f1_4
	v_cndmask_b32_e64 v18, v194, v18, s[72:73]
	v_cndmask_b32_e64 v19, v194, v19, s[74:75]
	v_cndmask_b32_e64 v20, v194, v20, s[76:77]
	v_cndmask_b32_e64 v21, v194, v21, s[78:79]
	s_branch .Lsel_f1_done
.Lsel_f1_4:
	s_cmpk_lg_u32 s6, 5
	s_cbranch_scc1 .Lsel_f1_5
	v_cndmask_b32_e64 v22, v194, v22, s[72:73]
	v_cndmask_b32_e64 v23, v194, v23, s[74:75]
	v_cndmask_b32_e64 v24, v194, v24, s[76:77]
	v_cndmask_b32_e64 v25, v194, v25, s[78:79]
	s_branch .Lsel_f1_done
.Lsel_f1_5:
	s_cmpk_lg_u32 s6, 6
	s_cbranch_scc1 .Lsel_f1_6
	v_cndmask_b32_e64 v26, v194, v26, s[72:73]
	v_cndmask_b32_e64 v27, v194, v27, s[74:75]
	v_cndmask_b32_e64 v28, v194, v28, s[76:77]
	v_cndmask_b32_e64 v29, v194, v29, s[78:79]
	s_branch .Lsel_f1_done
.Lsel_f1_6:
	s_cmpk_lg_u32 s6, 7
	s_cbranch_scc1 .Lsel_f1_7
	v_cndmask_b32_e64 v30, v194, v30, s[72:73]
	v_cndmask_b32_e64 v31, v194, v31, s[74:75]
	v_cndmask_b32_e64 v32, v194, v32, s[76:77]
	v_cndmask_b32_e64 v33, v194, v33, s[78:79]
	s_branch .Lsel_f1_done
.Lsel_f1_7:
.Lsel_f1_done:
	v_min3_f32 v234, v2, v3, v4
	v_max3_f32 v235, v2, v3, v4
	v_min_f32_e32 v234, v234, v5
	v_max_f32_e32 v235, v235, v5
	v_min3_f32 v234, v234, v6, v7
	v_max3_f32 v235, v235, v6, v7
	v_min3_f32 v234, v234, v8, v9
	v_max3_f32 v235, v235, v8, v9
	s_cmpk_lt_u32 s6, 2
	s_cbranch_scc1 .Lsel_A_done
	v_min3_f32 v234, v234, v10, v11
	v_max3_f32 v235, v235, v10, v11
	v_min3_f32 v234, v234, v12, v13
	v_max3_f32 v235, v235, v12, v13
	s_cmpk_lt_u32 s6, 3
	s_cbranch_scc1 .Lsel_A_done
	v_min3_f32 v234, v234, v14, v15
	v_max3_f32 v235, v235, v14, v15
	v_min3_f32 v234, v234, v16, v17
	v_max3_f32 v235, v235, v16, v17
	s_cmpk_lt_u32 s6, 4
	s_cbranch_scc1 .Lsel_A_done
	v_min3_f32 v234, v234, v18, v19
	v_max3_f32 v235, v235, v18, v19
	v_min3_f32 v234, v234, v20, v21
	v_max3_f32 v235, v235, v20, v21
	s_cmpk_lt_u32 s6, 5
	s_cbranch_scc1 .Lsel_A_done
	v_min3_f32 v234, v234, v22, v23
	v_max3_f32 v235, v235, v22, v23
	v_min3_f32 v234, v234, v24, v25
	v_max3_f32 v235, v235, v24, v25
	s_cmpk_lt_u32 s6, 6
	s_cbranch_scc1 .Lsel_A_done
	v_min3_f32 v234, v234, v26, v27
	v_max3_f32 v235, v235, v26, v27
	v_min3_f32 v234, v234, v28, v29
	v_max3_f32 v235, v235, v28, v29
	s_cmpk_lt_u32 s6, 7
	s_cbranch_scc1 .Lsel_A_done
	v_min3_f32 v234, v234, v30, v31
	v_max3_f32 v235, v235, v30, v31
	v_min3_f32 v234, v234, v32, v33
	v_max3_f32 v235, v235, v32, v33
.Lsel_A_done:
	v_xor_b32_e32 v238, 0x80000000, v234
	s_nop 0
	v_max_f32_dpp v235, v235, v235 quad_perm:[1,0,3,2] row_mask:0xf bank_mask:0xf
	v_max_f32_dpp v238, v238, v238 quad_perm:[1,0,3,2] row_mask:0xf bank_mask:0xf
	s_nop 0
	v_max_f32_dpp v235, v235, v235 quad_perm:[2,3,0,1] row_mask:0xf bank_mask:0xf
	v_max_f32_dpp v238, v238, v238 quad_perm:[2,3,0,1] row_mask:0xf bank_mask:0xf
	s_nop 0
	v_max_f32_dpp v235, v235, v235 row_half_mirror row_mask:0xf bank_mask:0xf
	v_max_f32_dpp v238, v238, v238 row_half_mirror row_mask:0xf bank_mask:0xf
	s_nop 0
	v_max_f32_dpp v235, v235, v235 row_mirror row_mask:0xf bank_mask:0xf
	v_max_f32_dpp v238, v238, v238 row_mirror row_mask:0xf bank_mask:0xf
	s_nop 0
	v_max_f32_dpp v235, v235, v235 row_bcast:15 row_mask:0xa bank_mask:0xf
	v_max_f32_dpp v238, v238, v238 row_bcast:15 row_mask:0xa bank_mask:0xf
	s_nop 0
	v_max_f32_dpp v235, v235, v235 row_bcast:31 row_mask:0xc bank_mask:0xf
	v_max_f32_dpp v238, v238, v238 row_bcast:31 row_mask:0xc bank_mask:0xf
	v_readlane_b32 s0, v235, 63
	v_readlane_b32 s1, v238, 63
	s_nop 0
	v_mov_b32_e32 v235, s0
	v_mov_b32_e32 v238, s1
	v_add_f32_e32 v239, v235, v238
	v_xor_b32_e32 v234, 0x80000000, v238
	v_rcp_f32_e32 v236, v239
	v_cmp_lt_f32_e32 vcc, 0x1e3ce508, v239
	v_mul_f32_e32 v236, 0x477fff80, v236
	s_nop 0
	v_cndmask_b32_e32 v236, 0, v236, vcc
	s_cmpk_lg_u32 s6, 1
	s_cbranch_scc1 .Lsel_f2_1
	v_cndmask_b32_e64 v6, v234, v6, s[72:73]
	v_cndmask_b32_e64 v7, v234, v7, s[74:75]
	v_cndmask_b32_e64 v8, v234, v8, s[76:77]
	v_cndmask_b32_e64 v9, v234, v9, s[78:79]
	s_branch .Lsel_f2_done
.Lsel_f2_1:
	s_cmpk_lg_u32 s6, 2
	s_cbranch_scc1 .Lsel_f2_2
	v_cndmask_b32_e64 v10, v234, v10, s[72:73]
	v_cndmask_b32_e64 v11, v234, v11, s[74:75]
	v_cndmask_b32_e64 v12, v234, v12, s[76:77]
	v_cndmask_b32_e64 v13, v234, v13, s[78:79]
	s_branch .Lsel_f2_done
.Lsel_f2_2:
	s_cmpk_lg_u32 s6, 3
	s_cbranch_scc1 .Lsel_f2_3
	v_cndmask_b32_e64 v14, v234, v14, s[72:73]
	v_cndmask_b32_e64 v15, v234, v15, s[74:75]
	v_cndmask_b32_e64 v16, v234, v16, s[76:77]
	v_cndmask_b32_e64 v17, v234, v17, s[78:79]
	s_branch .Lsel_f2_done
.Lsel_f2_3:
	s_cmpk_lg_u32 s6, 4
	s_cbranch_scc1 .Lsel_f2_4
	v_cndmask_b32_e64 v18, v234, v18, s[72:73]
	v_cndmask_b32_e64 v19, v234, v19, s[74:75]
	v_cndmask_b32_e64 v20, v234, v20, s[76:77]
	v_cndmask_b32_e64 v21, v234, v21, s[78:79]
	s_branch .Lsel_f2_done
.Lsel_f2_4:
	s_cmpk_lg_u32 s6, 5
	s_cbranch_scc1 .Lsel_f2_5
	v_cndmask_b32_e64 v22, v234, v22, s[72:73]
	v_cndmask_b32_e64 v23, v234, v23, s[74:75]
	v_cndmask_b32_e64 v24, v234, v24, s[76:77]
	v_cndmask_b32_e64 v25, v234, v25, s[78:79]
	s_branch .Lsel_f2_done
.Lsel_f2_5:
	s_cmpk_lg_u32 s6, 6
	s_cbranch_scc1 .Lsel_f2_6
	v_cndmask_b32_e64 v26, v234, v26, s[72:73]
	v_cndmask_b32_e64 v27, v234, v27, s[74:75]
	v_cndmask_b32_e64 v28, v234, v28, s[76:77]
	v_cndmask_b32_e64 v29, v234, v29, s[78:79]
	s_branch .Lsel_f2_done
.Lsel_f2_6:
	s_cmpk_lg_u32 s6, 7
	s_cbranch_scc1 .Lsel_f2_7
	v_cndmask_b32_e64 v30, v234, v30, s[72:73]
	v_cndmask_b32_e64 v31, v234, v31, s[74:75]
	v_cndmask_b32_e64 v32, v234, v32, s[76:77]
	v_cndmask_b32_e64 v33, v234, v33, s[78:79]
	s_branch .Lsel_f2_done
.Lsel_f2_7:
.Lsel_f2_done:
	v_sub_f32_e32 v199, v2, v234
	v_sub_f32_e32 v200, v3, v234
	v_sub_f32_e32 v201, v4, v234
	v_sub_f32_e32 v202, v5, v234
	v_mul_f32_e32 v199, v199, v236
	v_mul_f32_e32 v200, v200, v236
	v_mul_f32_e32 v201, v201, v236
	v_mul_f32_e32 v202, v202, v236
	v_cvt_u32_f32_e32 v199, v199
	v_cvt_u32_f32_e32 v200, v200
	v_cvt_u32_f32_e32 v201, v201
	v_cvt_u32_f32_e32 v202, v202
	v_min_u32_e32 v199, 0xffff, v199
	v_min_u32_e32 v200, 0xffff, v200
	v_min_u32_e32 v201, 0xffff, v201
	v_min_u32_e32 v202, 0xffff, v202
	v_lshrrev_b32_e32 v186, 8, v199
	v_lshrrev_b32_e32 v187, 8, v200
	v_lshrrev_b32_e32 v192, 8, v201
	v_lshrrev_b32_e32 v193, 8, v202
	v_lshl_add_u32 v186, v186, 2, v232
	v_lshl_add_u32 v187, v187, 2, v232
	v_lshl_add_u32 v192, v192, 2, v232
	v_lshl_add_u32 v193, v193, 2, v232
	ds_add_u32 v186, v233
	ds_add_u32 v187, v233
	ds_add_u32 v192, v233
	ds_add_u32 v193, v233
	v_sub_f32_e32 v203, v6, v234
	v_sub_f32_e32 v204, v7, v234
	v_sub_f32_e32 v205, v8, v234
	v_sub_f32_e32 v206, v9, v234
	v_mul_f32_e32 v203, v203, v236
	v_mul_f32_e32 v204, v204, v236
	v_mul_f32_e32 v205, v205, v236
	v_mul_f32_e32 v206, v206, v236
	v_cvt_u32_f32_e32 v203, v203
	v_cvt_u32_f32_e32 v204, v204
	v_cvt_u32_f32_e32 v205, v205
	v_cvt_u32_f32_e32 v206, v206
	v_min_u32_e32 v203, 0xffff, v203
	v_min_u32_e32 v204, 0xffff, v204
	v_min_u32_e32 v205, 0xffff, v205
	v_min_u32_e32 v206, 0xffff, v206
	v_lshrrev_b32_e32 v186, 8, v203
	v_lshrrev_b32_e32 v187, 8, v204
	v_lshrrev_b32_e32 v192, 8, v205
	v_lshrrev_b32_e32 v193, 8, v206
	v_lshl_add_u32 v186, v186, 2, v232
	v_lshl_add_u32 v187, v187, 2, v232
	v_lshl_add_u32 v192, v192, 2, v232
	v_lshl_add_u32 v193, v193, 2, v232
	ds_add_u32 v186, v233
	ds_add_u32 v187, v233
	ds_add_u32 v192, v233
	ds_add_u32 v193, v233
	s_cmpk_lt_u32 s6, 2
	s_cbranch_scc1 .Lsel_B_done
	v_sub_f32_e32 v207, v10, v234
	v_sub_f32_e32 v208, v11, v234
	v_sub_f32_e32 v209, v12, v234
	v_sub_f32_e32 v210, v13, v234
	v_mul_f32_e32 v207, v207, v236
	v_mul_f32_e32 v208, v208, v236
	v_mul_f32_e32 v209, v209, v236
	v_mul_f32_e32 v210, v210, v236
	v_cvt_u32_f32_e32 v207, v207
	v_cvt_u32_f32_e32 v208, v208
	v_cvt_u32_f32_e32 v209, v209
	v_cvt_u32_f32_e32 v210, v210
	v_min_u32_e32 v207, 0xffff, v207
	v_min_u32_e32 v208, 0xffff, v208
	v_min_u32_e32 v209, 0xffff, v209
	v_min_u32_e32 v210, 0xffff, v210
	v_lshrrev_b32_e32 v186, 8, v207
	v_lshrrev_b32_e32 v187, 8, v208
	v_lshrrev_b32_e32 v192, 8, v209
	v_lshrrev_b32_e32 v193, 8, v210
	v_lshl_add_u32 v186, v186, 2, v232
	v_lshl_add_u32 v187, v187, 2, v232
	v_lshl_add_u32 v192, v192, 2, v232
	v_lshl_add_u32 v193, v193, 2, v232
	ds_add_u32 v186, v233
	ds_add_u32 v187, v233
	ds_add_u32 v192, v233
	ds_add_u32 v193, v233
	s_cmpk_lt_u32 s6, 3
	s_cbranch_scc1 .Lsel_B_done
	v_sub_f32_e32 v211, v14, v234
	v_sub_f32_e32 v212, v15, v234
	v_sub_f32_e32 v213, v16, v234
	v_sub_f32_e32 v214, v17, v234
	v_mul_f32_e32 v211, v211, v236
	v_mul_f32_e32 v212, v212, v236
	v_mul_f32_e32 v213, v213, v236
	v_mul_f32_e32 v214, v214, v236
	v_cvt_u32_f32_e32 v211, v211
	v_cvt_u32_f32_e32 v212, v212
	v_cvt_u32_f32_e32 v213, v213
	v_cvt_u32_f32_e32 v214, v214
	v_min_u32_e32 v211, 0xffff, v211
	v_min_u32_e32 v212, 0xffff, v212
	v_min_u32_e32 v213, 0xffff, v213
	v_min_u32_e32 v214, 0xffff, v214
	v_lshrrev_b32_e32 v186, 8, v211
	v_lshrrev_b32_e32 v187, 8, v212
	v_lshrrev_b32_e32 v192, 8, v213
	v_lshrrev_b32_e32 v193, 8, v214
	v_lshl_add_u32 v186, v186, 2, v232
	v_lshl_add_u32 v187, v187, 2, v232
	v_lshl_add_u32 v192, v192, 2, v232
	v_lshl_add_u32 v193, v193, 2, v232
	ds_add_u32 v186, v233
	ds_add_u32 v187, v233
	ds_add_u32 v192, v233
	ds_add_u32 v193, v233
	s_cmpk_lt_u32 s6, 4
	s_cbranch_scc1 .Lsel_B_done
	v_sub_f32_e32 v215, v18, v234
	v_sub_f32_e32 v216, v19, v234
	v_sub_f32_e32 v217, v20, v234
	v_sub_f32_e32 v218, v21, v234
	v_mul_f32_e32 v215, v215, v236
	v_mul_f32_e32 v216, v216, v236
	v_mul_f32_e32 v217, v217, v236
	v_mul_f32_e32 v218, v218, v236
	v_cvt_u32_f32_e32 v215, v215
	v_cvt_u32_f32_e32 v216, v216
	v_cvt_u32_f32_e32 v217, v217
	v_cvt_u32_f32_e32 v218, v218
	v_min_u32_e32 v215, 0xffff, v215
	v_min_u32_e32 v216, 0xffff, v216
	v_min_u32_e32 v217, 0xffff, v217
	v_min_u32_e32 v218, 0xffff, v218
	v_lshrrev_b32_e32 v186, 8, v215
	v_lshrrev_b32_e32 v187, 8, v216
	v_lshrrev_b32_e32 v192, 8, v217
	v_lshrrev_b32_e32 v193, 8, v218
	v_lshl_add_u32 v186, v186, 2, v232
	v_lshl_add_u32 v187, v187, 2, v232
	v_lshl_add_u32 v192, v192, 2, v232
	v_lshl_add_u32 v193, v193, 2, v232
	ds_add_u32 v186, v233
	ds_add_u32 v187, v233
	ds_add_u32 v192, v233
	ds_add_u32 v193, v233
	s_cmpk_lt_u32 s6, 5
	s_cbranch_scc1 .Lsel_B_done
	v_sub_f32_e32 v219, v22, v234
	v_sub_f32_e32 v220, v23, v234
	v_sub_f32_e32 v221, v24, v234
	v_sub_f32_e32 v222, v25, v234
	v_mul_f32_e32 v219, v219, v236
	v_mul_f32_e32 v220, v220, v236
	v_mul_f32_e32 v221, v221, v236
	v_mul_f32_e32 v222, v222, v236
	v_cvt_u32_f32_e32 v219, v219
	v_cvt_u32_f32_e32 v220, v220
	v_cvt_u32_f32_e32 v221, v221
	v_cvt_u32_f32_e32 v222, v222
	v_min_u32_e32 v219, 0xffff, v219
	v_min_u32_e32 v220, 0xffff, v220
	v_min_u32_e32 v221, 0xffff, v221
	v_min_u32_e32 v222, 0xffff, v222
	v_lshrrev_b32_e32 v186, 8, v219
	v_lshrrev_b32_e32 v187, 8, v220
	v_lshrrev_b32_e32 v192, 8, v221
	v_lshrrev_b32_e32 v193, 8, v222
	v_lshl_add_u32 v186, v186, 2, v232
	v_lshl_add_u32 v187, v187, 2, v232
	v_lshl_add_u32 v192, v192, 2, v232
	v_lshl_add_u32 v193, v193, 2, v232
	ds_add_u32 v186, v233
	ds_add_u32 v187, v233
	ds_add_u32 v192, v233
	ds_add_u32 v193, v233
	s_cmpk_lt_u32 s6, 6
	s_cbranch_scc1 .Lsel_B_done
	v_sub_f32_e32 v223, v26, v234
	v_sub_f32_e32 v224, v27, v234
	v_sub_f32_e32 v225, v28, v234
	v_sub_f32_e32 v226, v29, v234
	v_mul_f32_e32 v223, v223, v236
	v_mul_f32_e32 v224, v224, v236
	v_mul_f32_e32 v225, v225, v236
	v_mul_f32_e32 v226, v226, v236
	v_cvt_u32_f32_e32 v223, v223
	v_cvt_u32_f32_e32 v224, v224
	v_cvt_u32_f32_e32 v225, v225
	v_cvt_u32_f32_e32 v226, v226
	v_min_u32_e32 v223, 0xffff, v223
	v_min_u32_e32 v224, 0xffff, v224
	v_min_u32_e32 v225, 0xffff, v225
	v_min_u32_e32 v226, 0xffff, v226
	v_lshrrev_b32_e32 v186, 8, v223
	v_lshrrev_b32_e32 v187, 8, v224
	v_lshrrev_b32_e32 v192, 8, v225
	v_lshrrev_b32_e32 v193, 8, v226
	v_lshl_add_u32 v186, v186, 2, v232
	v_lshl_add_u32 v187, v187, 2, v232
	v_lshl_add_u32 v192, v192, 2, v232
	v_lshl_add_u32 v193, v193, 2, v232
	ds_add_u32 v186, v233
	ds_add_u32 v187, v233
	ds_add_u32 v192, v233
	ds_add_u32 v193, v233
	s_cmpk_lt_u32 s6, 7
	s_cbranch_scc1 .Lsel_B_done
	v_sub_f32_e32 v227, v30, v234
	v_sub_f32_e32 v228, v31, v234
	v_sub_f32_e32 v229, v32, v234
	v_sub_f32_e32 v230, v33, v234
	v_mul_f32_e32 v227, v227, v236
	v_mul_f32_e32 v228, v228, v236
	v_mul_f32_e32 v229, v229, v236
	v_mul_f32_e32 v230, v230, v236
	v_cvt_u32_f32_e32 v227, v227
	v_cvt_u32_f32_e32 v228, v228
	v_cvt_u32_f32_e32 v229, v229
	v_cvt_u32_f32_e32 v230, v230
	v_min_u32_e32 v227, 0xffff, v227
	v_min_u32_e32 v228, 0xffff, v228
	v_min_u32_e32 v229, 0xffff, v229
	v_min_u32_e32 v230, 0xffff, v230
	v_lshrrev_b32_e32 v186, 8, v227
	v_lshrrev_b32_e32 v187, 8, v228
	v_lshrrev_b32_e32 v192, 8, v229
	v_lshrrev_b32_e32 v193, 8, v230
	v_lshl_add_u32 v186, v186, 2, v232
	v_lshl_add_u32 v187, v187, 2, v232
	v_lshl_add_u32 v192, v192, 2, v232
	v_lshl_add_u32 v193, v193, 2, v232
	ds_add_u32 v186, v233
	ds_add_u32 v187, v233
	ds_add_u32 v192, v233
	ds_add_u32 v193, v233
.Lsel_B_done:
	s_sub_i32 s0, s7, 0xff
	s_nop 1
	v_mov_b32_e32 v194, s0
	s_mov_b64 exec, 1
	ds_add_u32 v232, v194
	s_mov_b64 exec, -1
	s_mov_b32 s5, 1
	s_movk_i32 s81, 0x100
.Lsel_C:
	s_waitcnt lgkmcnt(0)
	v_lshl_add_u32 v186, v198, 4, v232
	ds_read_b128 v[188:191], v186
	s_waitcnt lgkmcnt(0)
	v_add3_u32 v192, v188, v189, v190
	v_add_u32_e32 v192, v192, v191
	s_nop 1
	v_add_u32_dpp v193, v192, v192 row_shr:1 row_mask:0xf bank_mask:0xf bound_ctrl:1
	s_nop 1
	v_add_u32_dpp v193, v193, v193 row_shr:2 row_mask:0xf bank_mask:0xf bound_ctrl:1
	s_nop 1
	v_add_u32_dpp v193, v193, v193 row_shr:4 row_mask:0xf bank_mask:0xf bound_ctrl:1
	s_nop 1
	v_add_u32_dpp v193, v193, v193 row_shr:8 row_mask:0xf bank_mask:0xf bound_ctrl:1
	s_nop 1
	v_add_u32_dpp v193, v193, v193 row_bcast:15 row_mask:0xa bank_mask:0xf
	s_nop 1
	v_add_u32_dpp v193, v193, v193 row_bcast:31 row_mask:0xc bank_mask:0xf
	s_nop 0
	v_readlane_b32 s0, v193, 63
	s_nop 1
	v_sub_u32_e32 v194, s0, v193
	v_add_u32_e32 v195, v194, v192
	v_cmp_gt_u32_e32 vcc, s81, v194
	v_cmp_le_u32_e64 s[0:1], s81, v195
	s_and_b64 s[0:1], s[0:1], vcc
	s_cmp_lg_u64 s[0:1], 0
	s_cbranch_scc0 .Lsel_bail
	s_ff1_i32_b64 s3, s[0:1]
	s_nop 1
	v_readlane_b32 s72, v188, s3
	v_readlane_b32 s73, v189, s3
	v_readlane_b32 s74, v190, s3
	v_readlane_b32 s75, v191, s3
	v_readlane_b32 s76, v194, s3
	s_lshl_b32 s80, s3, 2
	s_add_i32 s80, s80, 3
	s_mov_b32 s2, s76
	s_add_i32 s0, s76, s75
	s_cmp_ge_u32 s0, s81
	s_cbranch_scc1 .Lsel_C_found
	s_mov_b32 s2, s0
	s_add_i32 s80, s80, -1
	s_add_i32 s0, s0, s74
	s_cmp_ge_u32 s0, s81
	s_cbranch_scc1 .Lsel_C_found
	s_mov_b32 s2, s0
	s_add_i32 s80, s80, -1
	s_add_i32 s0, s0, s73
	s_cmp_ge_u32 s0, s81
	s_cbranch_scc1 .Lsel_C_found
	s_mov_b32 s2, s0
	s_add_i32 s80, s80, -1
.Lsel_C_found:
	s_sub_i32 s81, s81, s2
	s_cmp_eq_u32 s5, 2
	s_cbranch_scc1 .Lsel_C2
	s_cmp_eq_u32 s80, 0
	s_cbranch_scc1 .Lsel_bail
	s_lshl_b32 s83, s80, 8
	s_mov_b32 s7, 0xff00
	s_branch .Lsel_D
.Lsel_C2:
	s_or_b32 s83, s83, s80
	s_mov_b32 s7, 0xffff
.Lsel_D:
	v_mov_b32_e32 v195, 0
	v_mov_b32_e32 v196, 0
	v_and_b32_e32 v186, s7, v199
	v_and_b32_e32 v187, s7, v200
	v_and_b32_e32 v192, s7, v201
	v_and_b32_e32 v193, s7, v202
	v_cmp_eq_u32_e64 vcc, s83, v186
	v_cmp_eq_u32_e64 s[0:1], s83, v187
	v_cmp_eq_u32_e64 s[2:3], s83, v192
	v_cmp_eq_u32_e64 s[72:73], s83, v193
	v_addc_co_u32_e64 v195, vcc, 0, v195, vcc
	v_addc_co_u32_e64 v196, s[0:1], 0, v196, s[0:1]
	v_addc_co_u32_e64 v195, s[2:3], 0, v195, s[2:3]
	v_addc_co_u32_e64 v196, s[72:73], 0, v196, s[72:73]
	v_and_b32_e32 v186, s7, v203
	v_and_b32_e32 v187, s7, v204
	v_and_b32_e32 v192, s7, v205
	v_and_b32_e32 v193, s7, v206
	v_cmp_eq_u32_e64 vcc, s83, v186
	v_cmp_eq_u32_e64 s[0:1], s83, v187
	v_cmp_eq_u32_e64 s[2:3], s83, v192
	v_cmp_eq_u32_e64 s[72:73], s83, v193
	v_addc_co_u32_e64 v195, vcc, 0, v195, vcc
	v_addc_co_u32_e64 v196, s[0:1], 0, v196, s[0:1]
	v_addc_co_u32_e64 v195, s[2:3], 0, v195, s[2:3]
	v_addc_co_u32_e64 v196, s[72:73], 0, v196, s[72:73]
	s_cmpk_lt_u32 s6, 2
	s_cbranch_scc1 .Lsel_D_done
	v_and_b32_e32 v186, s7, v207
	v_and_b32_e32 v187, s7, v208
	v_and_b32_e32 v192, s7, v209
	v_and_b32_e32 v193, s7, v210
	v_cmp_eq_u32_e64 vcc, s83, v186
	v_cmp_eq_u32_e64 s[0:1], s83, v187
	v_cmp_eq_u32_e64 s[2:3], s83, v192
	v_cmp_eq_u32_e64 s[72:73], s83, v193
	v_addc_co_u32_e64 v195, vcc, 0, v195, vcc
	v_addc_co_u32_e64 v196, s[0:1], 0, v196, s[0:1]
	v_addc_co_u32_e64 v195, s[2:3], 0, v195, s[2:3]
	v_addc_co_u32_e64 v196, s[72:73], 0, v196, s[72:73]
	s_cmpk_lt_u32 s6, 3
	s_cbranch_scc1 .Lsel_D_done
	v_and_b32_e32 v186, s7, v211
	v_and_b32_e32 v187, s7, v212
	v_and_b32_e32 v192, s7, v213
	v_and_b32_e32 v193, s7, v214
	v_cmp_eq_u32_e64 vcc, s83, v186
	v_cmp_eq_u32_e64 s[0:1], s83, v187
	v_cmp_eq_u32_e64 s[2:3], s83, v192
	v_cmp_eq_u32_e64 s[72:73], s83, v193
	v_addc_co_u32_e64 v195, vcc, 0, v195, vcc
	v_addc_co_u32_e64 v196, s[0:1], 0, v196, s[0:1]
	v_addc_co_u32_e64 v195, s[2:3], 0, v195, s[2:3]
	v_addc_co_u32_e64 v196, s[72:73], 0, v196, s[72:73]
	s_cmpk_lt_u32 s6, 4
	s_cbranch_scc1 .Lsel_D_done
	v_and_b32_e32 v186, s7, v215
	v_and_b32_e32 v187, s7, v216
	v_and_b32_e32 v192, s7, v217
	v_and_b32_e32 v193, s7, v218
	v_cmp_eq_u32_e64 vcc, s83, v186
	v_cmp_eq_u32_e64 s[0:1], s83, v187
	v_cmp_eq_u32_e64 s[2:3], s83, v192
	v_cmp_eq_u32_e64 s[72:73], s83, v193
	v_addc_co_u32_e64 v195, vcc, 0, v195, vcc
	v_addc_co_u32_e64 v196, s[0:1], 0, v196, s[0:1]
	v_addc_co_u32_e64 v195, s[2:3], 0, v195, s[2:3]
	v_addc_co_u32_e64 v196, s[72:73], 0, v196, s[72:73]
	s_cmpk_lt_u32 s6, 5
	s_cbranch_scc1 .Lsel_D_done
	v_and_b32_e32 v186, s7, v219
	v_and_b32_e32 v187, s7, v220
	v_and_b32_e32 v192, s7, v221
	v_and_b32_e32 v193, s7, v222
	v_cmp_eq_u32_e64 vcc, s83, v186
	v_cmp_eq_u32_e64 s[0:1], s83, v187
	v_cmp_eq_u32_e64 s[2:3], s83, v192
	v_cmp_eq_u32_e64 s[72:73], s83, v193
	v_addc_co_u32_e64 v195, vcc, 0, v195, vcc
	v_addc_co_u32_e64 v196, s[0:1], 0, v196, s[0:1]
	v_addc_co_u32_e64 v195, s[2:3], 0, v195, s[2:3]
	v_addc_co_u32_e64 v196, s[72:73], 0, v196, s[72:73]
	s_cmpk_lt_u32 s6, 6
	s_cbranch_scc1 .Lsel_D_done
	v_and_b32_e32 v186, s7, v223
	v_and_b32_e32 v187, s7, v224
	v_and_b32_e32 v192, s7, v225
	v_and_b32_e32 v193, s7, v226
	v_cmp_eq_u32_e64 vcc, s83, v186
	v_cmp_eq_u32_e64 s[0:1], s83, v187
	v_cmp_eq_u32_e64 s[2:3], s83, v192
	v_cmp_eq_u32_e64 s[72:73], s83, v193
	v_addc_co_u32_e64 v195, vcc, 0, v195, vcc
	v_addc_co_u32_e64 v196, s[0:1], 0, v196, s[0:1]
	v_addc_co_u32_e64 v195, s[2:3], 0, v195, s[2:3]
	v_addc_co_u32_e64 v196, s[72:73], 0, v196, s[72:73]
	s_cmpk_lt_u32 s6, 7
	s_cbranch_scc1 .Lsel_D_done
	v_and_b32_e32 v186, s7, v227
	v_and_b32_e32 v187, s7, v228
	v_and_b32_e32 v192, s7, v229
	v_and_b32_e32 v193, s7, v230
	v_cmp_eq_u32_e64 vcc, s83, v186
	v_cmp_eq_u32_e64 s[0:1], s83, v187
	v_cmp_eq_u32_e64 s[2:3], s83, v192
	v_cmp_eq_u32_e64 s[72:73], s83, v193
	v_addc_co_u32_e64 v195, vcc, 0, v195, vcc
	v_addc_co_u32_e64 v196, s[0:1], 0, v196, s[0:1]
	v_addc_co_u32_e64 v195, s[2:3], 0, v195, s[2:3]
	v_addc_co_u32_e64 v196, s[72:73], 0, v196, s[72:73]
.Lsel_D_done:
	v_add_u32_e32 v195, v195, v196
	s_nop 1
	v_add_u32_dpp v197, v195, v195 row_shr:1 row_mask:0xf bank_mask:0xf bound_ctrl:1
	s_nop 1
	v_add_u32_dpp v197, v197, v197 row_shr:2 row_mask:0xf bank_mask:0xf bound_ctrl:1
	s_nop 1
	v_add_u32_dpp v197, v197, v197 row_shr:4 row_mask:0xf bank_mask:0xf bound_ctrl:1
	s_nop 1
	v_add_u32_dpp v197, v197, v197 row_shr:8 row_mask:0xf bank_mask:0xf bound_ctrl:1
	s_nop 1
	v_add_u32_dpp v197, v197, v197 row_bcast:15 row_mask:0xa bank_mask:0xf
	s_nop 1
	v_add_u32_dpp v197, v197, v197 row_bcast:31 row_mask:0xc bank_mask:0xf
	s_nop 0
	v_readlane_b32 s82, v197, 63
	v_sub_u32_e32 v239, v197, v195
	s_cmp_eq_u32 s82, s81
	s_cbranch_scc0 .Lsel_D_ne
	s_add_i32 s80, s83, -1
	s_branch .Lsel_E
.Lsel_D_ne:
	s_cmpk_le_u32 s82, 64
	s_cbranch_scc1 .Lsel_rank
	s_cmp_eq_u32 s5, 2
	s_cbranch_scc1 .Lsel_bail
	s_mov_b32 s5, 2
	v_lshl_add_u32 v186, v198, 4, v232
	v_mov_b32_e32 v188, 0
	v_mov_b32_e32 v189, 0
	v_mov_b32_e32 v190, 0
	v_mov_b32_e32 v191, 0
	ds_write_b128 v186, v[188:191]
	v_and_b32_e32 v186, s7, v199
	v_and_b32_e32 v187, s7, v200
	v_and_b32_e32 v192, s7, v201
	v_and_b32_e32 v193, s7, v202
	v_cmp_eq_u32_e64 s[0:1], s83, v186
	v_cmp_eq_u32_e64 s[2:3], s83, v187
	v_cmp_eq_u32_e64 s[72:73], s83, v192
	v_cmp_eq_u32_e64 s[74:75], s83, v193
	v_and_b32_e32 v240, 0xff, v199
	v_and_b32_e32 v241, 0xff, v200
	v_and_b32_e32 v242, 0xff, v201
	v_and_b32_e32 v243, 0xff, v202
	v_lshl_add_u32 v240, v240, 2, v232
	v_lshl_add_u32 v241, v241, 2, v232
	v_lshl_add_u32 v242, v242, 2, v232
	v_lshl_add_u32 v243, v243, 2, v232
	s_mov_b64 exec, s[0:1]
	ds_add_u32 v240, v233
	s_mov_b64 exec, s[2:3]
	ds_add_u32 v241, v233
	s_mov_b64 exec, s[72:73]
	ds_add_u32 v242, v233
	s_mov_b64 exec, s[74:75]
	ds_add_u32 v243, v233
	s_mov_b64 exec, -1
	v_and_b32_e32 v186, s7, v203
	v_and_b32_e32 v187, s7, v204
	v_and_b32_e32 v192, s7, v205
	v_and_b32_e32 v193, s7, v206
	v_cmp_eq_u32_e64 s[0:1], s83, v186
	v_cmp_eq_u32_e64 s[2:3], s83, v187
	v_cmp_eq_u32_e64 s[72:73], s83, v192
	v_cmp_eq_u32_e64 s[74:75], s83, v193
	v_and_b32_e32 v240, 0xff, v203
	v_and_b32_e32 v241, 0xff, v204
	v_and_b32_e32 v242, 0xff, v205
	v_and_b32_e32 v243, 0xff, v206
	v_lshl_add_u32 v240, v240, 2, v232
	v_lshl_add_u32 v241, v241, 2, v232
	v_lshl_add_u32 v242, v242, 2, v232
	v_lshl_add_u32 v243, v243, 2, v232
	s_mov_b64 exec, s[0:1]
	ds_add_u32 v240, v233
	s_mov_b64 exec, s[2:3]
	ds_add_u32 v241, v233
	s_mov_b64 exec, s[72:73]
	ds_add_u32 v242, v233
	s_mov_b64 exec, s[74:75]
	ds_add_u32 v243, v233
	s_mov_b64 exec, -1
	s_cmpk_lt_u32 s6, 2
	s_cbranch_scc1 .Lsel_B2_done
	v_and_b32_e32 v186, s7, v207
	v_and_b32_e32 v187, s7, v208
	v_and_b32_e32 v192, s7, v209
	v_and_b32_e32 v193, s7, v210
	v_cmp_eq_u32_e64 s[0:1], s83, v186
	v_cmp_eq_u32_e64 s[2:3], s83, v187
	v_cmp_eq_u32_e64 s[72:73], s83, v192
	v_cmp_eq_u32_e64 s[74:75], s83, v193
	v_and_b32_e32 v240, 0xff, v207
	v_and_b32_e32 v241, 0xff, v208
	v_and_b32_e32 v242, 0xff, v209
	v_and_b32_e32 v243, 0xff, v210
	v_lshl_add_u32 v240, v240, 2, v232
	v_lshl_add_u32 v241, v241, 2, v232
	v_lshl_add_u32 v242, v242, 2, v232
	v_lshl_add_u32 v243, v243, 2, v232
	s_mov_b64 exec, s[0:1]
	ds_add_u32 v240, v233
	s_mov_b64 exec, s[2:3]
	ds_add_u32 v241, v233
	s_mov_b64 exec, s[72:73]
	ds_add_u32 v242, v233
	s_mov_b64 exec, s[74:75]
	ds_add_u32 v243, v233
	s_mov_b64 exec, -1
	s_cmpk_lt_u32 s6, 3
	s_cbranch_scc1 .Lsel_B2_done
	v_and_b32_e32 v186, s7, v211
	v_and_b32_e32 v187, s7, v212
	v_and_b32_e32 v192, s7, v213
	v_and_b32_e32 v193, s7, v214
	v_cmp_eq_u32_e64 s[0:1], s83, v186
	v_cmp_eq_u32_e64 s[2:3], s83, v187
	v_cmp_eq_u32_e64 s[72:73], s83, v192
	v_cmp_eq_u32_e64 s[74:75], s83, v193
	v_and_b32_e32 v240, 0xff, v211
	v_and_b32_e32 v241, 0xff, v212
	v_and_b32_e32 v242, 0xff, v213
	v_and_b32_e32 v243, 0xff, v214
	v_lshl_add_u32 v240, v240, 2, v232
	v_lshl_add_u32 v241, v241, 2, v232
	v_lshl_add_u32 v242, v242, 2, v232
	v_lshl_add_u32 v243, v243, 2, v232
	s_mov_b64 exec, s[0:1]
	ds_add_u32 v240, v233
	s_mov_b64 exec, s[2:3]
	ds_add_u32 v241, v233
	s_mov_b64 exec, s[72:73]
	ds_add_u32 v242, v233
	s_mov_b64 exec, s[74:75]
	ds_add_u32 v243, v233
	s_mov_b64 exec, -1
	s_cmpk_lt_u32 s6, 4
	s_cbranch_scc1 .Lsel_B2_done
	v_and_b32_e32 v186, s7, v215
	v_and_b32_e32 v187, s7, v216
	v_and_b32_e32 v192, s7, v217
	v_and_b32_e32 v193, s7, v218
	v_cmp_eq_u32_e64 s[0:1], s83, v186
	v_cmp_eq_u32_e64 s[2:3], s83, v187
	v_cmp_eq_u32_e64 s[72:73], s83, v192
	v_cmp_eq_u32_e64 s[74:75], s83, v193
	v_and_b32_e32 v240, 0xff, v215
	v_and_b32_e32 v241, 0xff, v216
	v_and_b32_e32 v242, 0xff, v217
	v_and_b32_e32 v243, 0xff, v218
	v_lshl_add_u32 v240, v240, 2, v232
	v_lshl_add_u32 v241, v241, 2, v232
	v_lshl_add_u32 v242, v242, 2, v232
	v_lshl_add_u32 v243, v243, 2, v232
	s_mov_b64 exec, s[0:1]
	ds_add_u32 v240, v233
	s_mov_b64 exec, s[2:3]
	ds_add_u32 v241, v233
	s_mov_b64 exec, s[72:73]
	ds_add_u32 v242, v233
	s_mov_b64 exec, s[74:75]
	ds_add_u32 v243, v233
	s_mov_b64 exec, -1
	s_cmpk_lt_u32 s6, 5
	s_cbranch_scc1 .Lsel_B2_done
	v_and_b32_e32 v186, s7, v219
	v_and_b32_e32 v187, s7, v220
	v_and_b32_e32 v192, s7, v221
	v_and_b32_e32 v193, s7, v222
	v_cmp_eq_u32_e64 s[0:1], s83, v186
	v_cmp_eq_u32_e64 s[2:3], s83, v187
	v_cmp_eq_u32_e64 s[72:73], s83, v192
	v_cmp_eq_u32_e64 s[74:75], s83, v193
	v_and_b32_e32 v240, 0xff, v219
	v_and_b32_e32 v241, 0xff, v220
	v_and_b32_e32 v242, 0xff, v221
	v_and_b32_e32 v243, 0xff, v222
	v_lshl_add_u32 v240, v240, 2, v232
	v_lshl_add_u32 v241, v241, 2, v232
	v_lshl_add_u32 v242, v242, 2, v232
	v_lshl_add_u32 v243, v243, 2, v232
	s_mov_b64 exec, s[0:1]
	ds_add_u32 v240, v233
	s_mov_b64 exec, s[2:3]
	ds_add_u32 v241, v233
	s_mov_b64 exec, s[72:73]
	ds_add_u32 v242, v233
	s_mov_b64 exec, s[74:75]
	ds_add_u32 v243, v233
	s_mov_b64 exec, -1
	s_cmpk_lt_u32 s6, 6
	s_cbranch_scc1 .Lsel_B2_done
	v_and_b32_e32 v186, s7, v223
	v_and_b32_e32 v187, s7, v224
	v_and_b32_e32 v192, s7, v225
	v_and_b32_e32 v193, s7, v226
	v_cmp_eq_u32_e64 s[0:1], s83, v186
	v_cmp_eq_u32_e64 s[2:3], s83, v187
	v_cmp_eq_u32_e64 s[72:73], s83, v192
	v_cmp_eq_u32_e64 s[74:75], s83, v193
	v_and_b32_e32 v240, 0xff, v223
	v_and_b32_e32 v241, 0xff, v224
	v_and_b32_e32 v242, 0xff, v225
	v_and_b32_e32 v243, 0xff, v226
	v_lshl_add_u32 v240, v240, 2, v232
	v_lshl_add_u32 v241, v241, 2, v232
	v_lshl_add_u32 v242, v242, 2, v232
	v_lshl_add_u32 v243, v243, 2, v232
	s_mov_b64 exec, s[0:1]
	ds_add_u32 v240, v233
	s_mov_b64 exec, s[2:3]
	ds_add_u32 v241, v233
	s_mov_b64 exec, s[72:73]
	ds_add_u32 v242, v233
	s_mov_b64 exec, s[74:75]
	ds_add_u32 v243, v233
	s_mov_b64 exec, -1
	s_cmpk_lt_u32 s6, 7
	s_cbranch_scc1 .Lsel_B2_done
	v_and_b32_e32 v186, s7, v227
	v_and_b32_e32 v187, s7, v228
	v_and_b32_e32 v192, s7, v229
	v_and_b32_e32 v193, s7, v230
	v_cmp_eq_u32_e64 s[0:1], s83, v186
	v_cmp_eq_u32_e64 s[2:3], s83, v187
	v_cmp_eq_u32_e64 s[72:73], s83, v192
	v_cmp_eq_u32_e64 s[74:75], s83, v193
	v_and_b32_e32 v240, 0xff, v227
	v_and_b32_e32 v241, 0xff, v228
	v_and_b32_e32 v242, 0xff, v229
	v_and_b32_e32 v243, 0xff, v230
	v_lshl_add_u32 v240, v240, 2, v232
	v_lshl_add_u32 v241, v241, 2, v232
	v_lshl_add_u32 v242, v242, 2, v232
	v_lshl_add_u32 v243, v243, 2, v232
	s_mov_b64 exec, s[0:1]
	ds_add_u32 v240, v233
	s_mov_b64 exec, s[2:3]
	ds_add_u32 v241, v233
	s_mov_b64 exec, s[72:73]
	ds_add_u32 v242, v233
	s_mov_b64 exec, s[74:75]
	ds_add_u32 v243, v233
	s_mov_b64 exec, -1

.Lsel_rank:
	s_xor_b32 s80, s7, 0xffff
	s_or_b32 s80, s80, s83
	s_and_b32 s4, s28, 7
	s_lshl_b32 s4, s4, 13
	s_add_i32 s4, s4, 0xc800
	s_nop 1
	v_lshl_add_u32 v240, v239, 3, s4
	v_and_b32_e32 v186, s7, v199
	v_and_b32_e32 v187, s7, v200
	v_and_b32_e32 v192, s7, v201
	v_and_b32_e32 v193, s7, v202
	v_cmp_eq_u32_e64 s[0:1], s83, v186
	v_cmp_eq_u32_e64 s[2:3], s83, v187
	v_cmp_eq_u32_e64 s[72:73], s83, v192
	v_cmp_eq_u32_e64 s[74:75], s83, v193
	v_add_u32_e32 v241, 0, v231
	v_add_u32_e32 v242, 1, v231
	v_add_u32_e32 v243, 2, v231
	v_add_u32_e32 v248, 3, v231
	s_mov_b64 exec, s[0:1]
	ds_write2_b32 v240, v241, v2 offset1:1
	v_add_u32_e32 v240, 8, v240
	s_mov_b64 exec, s[2:3]
	ds_write2_b32 v240, v242, v3 offset1:1
	v_add_u32_e32 v240, 8, v240
	s_mov_b64 exec, s[72:73]
	ds_write2_b32 v240, v243, v4 offset1:1
	v_add_u32_e32 v240, 8, v240
	s_mov_b64 exec, s[74:75]
	ds_write2_b32 v240, v248, v5 offset1:1
	v_add_u32_e32 v240, 8, v240
	s_mov_b64 exec, -1
	v_and_b32_e32 v186, s7, v203
	v_and_b32_e32 v187, s7, v204
	v_and_b32_e32 v192, s7, v205
	v_and_b32_e32 v193, s7, v206
	v_cmp_eq_u32_e64 s[0:1], s83, v186
	v_cmp_eq_u32_e64 s[2:3], s83, v187
	v_cmp_eq_u32_e64 s[72:73], s83, v192
	v_cmp_eq_u32_e64 s[74:75], s83, v193
	v_add_u32_e32 v241, 0x100, v231
	v_add_u32_e32 v242, 0x101, v231
	v_add_u32_e32 v243, 0x102, v231
	v_add_u32_e32 v248, 0x103, v231
	s_mov_b64 exec, s[0:1]
	ds_write2_b32 v240, v241, v6 offset1:1
	v_add_u32_e32 v240, 8, v240
	s_mov_b64 exec, s[2:3]
	ds_write2_b32 v240, v242, v7 offset1:1
	v_add_u32_e32 v240, 8, v240
	s_mov_b64 exec, s[72:73]
	ds_write2_b32 v240, v243, v8 offset1:1
	v_add_u32_e32 v240, 8, v240
	s_mov_b64 exec, s[74:75]
	ds_write2_b32 v240, v248, v9 offset1:1
	v_add_u32_e32 v240, 8, v240
	s_mov_b64 exec, -1
	s_cmpk_lt_u32 s6, 2
	s_cbranch_scc1 .Lsel_D2_done
	v_and_b32_e32 v186, s7, v207
	v_and_b32_e32 v187, s7, v208
	v_and_b32_e32 v192, s7, v209
	v_and_b32_e32 v193, s7, v210
	v_cmp_eq_u32_e64 s[0:1], s83, v186
	v_cmp_eq_u32_e64 s[2:3], s83, v187
	v_cmp_eq_u32_e64 s[72:73], s83, v192
	v_cmp_eq_u32_e64 s[74:75], s83, v193
	v_add_u32_e32 v241, 0x200, v231
	v_add_u32_e32 v242, 0x201, v231
	v_add_u32_e32 v243, 0x202, v231
	v_add_u32_e32 v248, 0x203, v231
	s_mov_b64 exec, s[0:1]
	ds_write2_b32 v240, v241, v10 offset1:1
	v_add_u32_e32 v240, 8, v240
	s_mov_b64 exec, s[2:3]
	ds_write2_b32 v240, v242, v11 offset1:1
	v_add_u32_e32 v240, 8, v240
	s_mov_b64 exec, s[72:73]
	ds_write2_b32 v240, v243, v12 offset1:1
	v_add_u32_e32 v240, 8, v240
	s_mov_b64 exec, s[74:75]
	ds_write2_b32 v240, v248, v13 offset1:1
	v_add_u32_e32 v240, 8, v240
	s_mov_b64 exec, -1
	s_cmpk_lt_u32 s6, 3
	s_cbranch_scc1 .Lsel_D2_done
	v_and_b32_e32 v186, s7, v211
	v_and_b32_e32 v187, s7, v212
	v_and_b32_e32 v192, s7, v213
	v_and_b32_e32 v193, s7, v214
	v_cmp_eq_u32_e64 s[0:1], s83, v186
	v_cmp_eq_u32_e64 s[2:3], s83, v187
	v_cmp_eq_u32_e64 s[72:73], s83, v192
	v_cmp_eq_u32_e64 s[74:75], s83, v193
	v_add_u32_e32 v241, 0x300, v231
	v_add_u32_e32 v242, 0x301, v231
	v_add_u32_e32 v243, 0x302, v231
	v_add_u32_e32 v248, 0x303, v231
	s_mov_b64 exec, s[0:1]
	ds_write2_b32 v240, v241, v14 offset1:1
	v_add_u32_e32 v240, 8, v240
	s_mov_b64 exec, s[2:3]
	ds_write2_b32 v240, v242, v15 offset1:1
	v_add_u32_e32 v240, 8, v240
	s_mov_b64 exec, s[72:73]
	ds_write2_b32 v240, v243, v16 offset1:1
	v_add_u32_e32 v240, 8, v240
	s_mov_b64 exec, s[74:75]
	ds_write2_b32 v240, v248, v17 offset1:1
	v_add_u32_e32 v240, 8, v240
	s_mov_b64 exec, -1
	s_cmpk_lt_u32 s6, 4
	s_cbranch_scc1 .Lsel_D2_done
	v_and_b32_e32 v186, s7, v215
	v_and_b32_e32 v187, s7, v216
	v_and_b32_e32 v192, s7, v217
	v_and_b32_e32 v193, s7, v218
	v_cmp_eq_u32_e64 s[0:1], s83, v186
	v_cmp_eq_u32_e64 s[2:3], s83, v187
	v_cmp_eq_u32_e64 s[72:73], s83, v192
	v_cmp_eq_u32_e64 s[74:75], s83, v193
	v_add_u32_e32 v241, 0x400, v231
	v_add_u32_e32 v242, 0x401, v231
	v_add_u32_e32 v243, 0x402, v231
	v_add_u32_e32 v248, 0x403, v231
	s_mov_b64 exec, s[0:1]
	ds_write2_b32 v240, v241, v18 offset1:1
	v_add_u32_e32 v240, 8, v240
	s_mov_b64 exec, s[2:3]
	ds_write2_b32 v240, v242, v19 offset1:1
	v_add_u32_e32 v240, 8, v240
	s_mov_b64 exec, s[72:73]
	ds_write2_b32 v240, v243, v20 offset1:1
	v_add_u32_e32 v240, 8, v240
	s_mov_b64 exec, s[74:75]
	ds_write2_b32 v240, v248, v21 offset1:1
	v_add_u32_e32 v240, 8, v240
	s_mov_b64 exec, -1
	s_cmpk_lt_u32 s6, 5
	s_cbranch_scc1 .Lsel_D2_done
	v_and_b32_e32 v186, s7, v219
	v_and_b32_e32 v187, s7, v220
	v_and_b32_e32 v192, s7, v221
	v_and_b32_e32 v193, s7, v222
	v_cmp_eq_u32_e64 s[0:1], s83, v186
	v_cmp_eq_u32_e64 s[2:3], s83, v187
	v_cmp_eq_u32_e64 s[72:73], s83, v192
	v_cmp_eq_u32_e64 s[74:75], s83, v193
	v_add_u32_e32 v241, 0x500, v231
	v_add_u32_e32 v242, 0x501, v231
	v_add_u32_e32 v243, 0x502, v231
	v_add_u32_e32 v248, 0x503, v231
	s_mov_b64 exec, s[0:1]
	ds_write2_b32 v240, v241, v22 offset1:1
	v_add_u32_e32 v240, 8, v240
	s_mov_b64 exec, s[2:3]
	ds_write2_b32 v240, v242, v23 offset1:1
	v_add_u32_e32 v240, 8, v240
	s_mov_b64 exec, s[72:73]
	ds_write2_b32 v240, v243, v24 offset1:1
	v_add_u32_e32 v240, 8, v240
	s_mov_b64 exec, s[74:75]
	ds_write2_b32 v240, v248, v25 offset1:1
	v_add_u32_e32 v240, 8, v240
	s_mov_b64 exec, -1
	s_cmpk_lt_u32 s6, 6
	s_cbranch_scc1 .Lsel_D2_done
	v_and_b32_e32 v186, s7, v223
	v_and_b32_e32 v187, s7, v224
	v_and_b32_e32 v192, s7, v225
	v_and_b32_e32 v193, s7, v226
	v_cmp_eq_u32_e64 s[0:1], s83, v186
	v_cmp_eq_u32_e64 s[2:3], s83, v187
	v_cmp_eq_u32_e64 s[72:73], s83, v192
	v_cmp_eq_u32_e64 s[74:75], s83, v193
	v_add_u32_e32 v241, 0x600, v231
	v_add_u32_e32 v242, 0x601, v231
	v_add_u32_e32 v243, 0x602, v231
	v_add_u32_e32 v248, 0x603, v231
	s_mov_b64 exec, s[0:1]
	ds_write2_b32 v240, v241, v26 offset1:1
	v_add_u32_e32 v240, 8, v240
	s_mov_b64 exec, s[2:3]
	ds_write2_b32 v240, v242, v27 offset1:1
	v_add_u32_e32 v240, 8, v240
	s_mov_b64 exec, s[72:73]
	ds_write2_b32 v240, v243, v28 offset1:1
	v_add_u32_e32 v240, 8, v240
	s_mov_b64 exec, s[74:75]
	ds_write2_b32 v240, v248, v29 offset1:1
	v_add_u32_e32 v240, 8, v240
	s_mov_b64 exec, -1
	s_cmpk_lt_u32 s6, 7
	s_cbranch_scc1 .Lsel_D2_done
	v_and_b32_e32 v186, s7, v227
	v_and_b32_e32 v187, s7, v228
	v_and_b32_e32 v192, s7, v229
	v_and_b32_e32 v193, s7, v230
	v_cmp_eq_u32_e64 s[0:1], s83, v186
	v_cmp_eq_u32_e64 s[2:3], s83, v187
	v_cmp_eq_u32_e64 s[72:73], s83, v192
	v_cmp_eq_u32_e64 s[74:75], s83, v193
	v_add_u32_e32 v241, 0x700, v231
	v_add_u32_e32 v242, 0x701, v231
	v_add_u32_e32 v243, 0x702, v231
	v_add_u32_e32 v248, 0x703, v231
	s_mov_b64 exec, s[0:1]
	ds_write2_b32 v240, v241, v30 offset1:1
	v_add_u32_e32 v240, 8, v240
	s_mov_b64 exec, s[2:3]
	ds_write2_b32 v240, v242, v31 offset1:1
	v_add_u32_e32 v240, 8, v240
	s_mov_b64 exec, s[72:73]
	ds_write2_b32 v240, v243, v32 offset1:1
	v_add_u32_e32 v240, 8, v240
	s_mov_b64 exec, s[74:75]
	ds_write2_b32 v240, v248, v33 offset1:1
	v_add_u32_e32 v240, 8, v240
	s_mov_b64 exec, -1
.Lsel_D2_done:
	s_waitcnt lgkmcnt(0)
	v_lshl_add_u32 v241, v198, 3, s4
	ds_read_b64 v[242:243], v241
	s_waitcnt lgkmcnt(0)
	v_mov_b32_e32 v248, v242
	v_add_f32_e32 v243, 0, v243
	v_ashrrev_i32_e32 v186, 31, v243
	v_or_b32_e32 v186, 0x80000000, v186
	v_xor_b32_e32 v243, v243, v186
	v_not_b32_e32 v242, v242
	v_cmp_gt_u32_e32 vcc, s82, v198
	v_mov_b32_e32 v249, 0
	v_mov_b32_e32 v187, 0
	v_cndmask_b32_e32 v243, 0, v243, vcc
	v_cndmask_b32_e32 v242, 0, v242, vcc
	s_nop 0
	v_readlane_b32 s72, v242, 0
	v_readlane_b32 s73, v243, 0
	v_readlane_b32 s74, v242, 1
	v_readlane_b32 s75, v243, 1
	v_readlane_b32 s76, v242, 2
	v_readlane_b32 s77, v243, 2
	v_readlane_b32 s78, v242, 3
	v_readlane_b32 s79, v243, 3
	v_cmp_gt_u64_e64 vcc, s[72:73], v[242:243]
	v_cmp_gt_u64_e64 s[0:1], s[74:75], v[242:243]
	v_cmp_gt_u64_e64 s[2:3], s[76:77], v[242:243]
	v_cmp_gt_u64_e64 s[4:5], s[78:79], v[242:243]
	v_addc_co_u32_e64 v249, vcc, 0, v249, vcc
	v_addc_co_u32_e64 v187, s[0:1], 0, v187, s[0:1]
	v_addc_co_u32_e64 v249, s[2:3], 0, v249, s[2:3]
	v_addc_co_u32_e64 v187, s[4:5], 0, v187, s[4:5]
	s_cmpk_le_u32 s82, 4
	s_cbranch_scc1 .Lsel_rank_done
	v_readlane_b32 s72, v242, 4
	v_readlane_b32 s73, v243, 4
	v_readlane_b32 s74, v242, 5
	v_readlane_b32 s75, v243, 5
	v_readlane_b32 s76, v242, 6
	v_readlane_b32 s77, v243, 6
	v_readlane_b32 s78, v242, 7
	v_readlane_b32 s79, v243, 7
	v_cmp_gt_u64_e64 vcc, s[72:73], v[242:243]
	v_cmp_gt_u64_e64 s[0:1], s[74:75], v[242:243]
	v_cmp_gt_u64_e64 s[2:3], s[76:77], v[242:243]
	v_cmp_gt_u64_e64 s[4:5], s[78:79], v[242:243]
	v_addc_co_u32_e64 v249, vcc, 0, v249, vcc
	v_addc_co_u32_e64 v187, s[0:1], 0, v187, s[0:1]
	v_addc_co_u32_e64 v249, s[2:3], 0, v249, s[2:3]
	v_addc_co_u32_e64 v187, s[4:5], 0, v187, s[4:5]
	s_cmpk_le_u32 s82, 8
	s_cbranch_scc1 .Lsel_rank_done
	v_readlane_b32 s72, v242, 8
	v_readlane_b32 s73, v243, 8
	v_readlane_b32 s74, v242, 9
	v_readlane_b32 s75, v243, 9
	v_readlane_b32 s76, v242, 10
	v_readlane_b32 s77, v243, 10
	v_readlane_b32 s78, v242, 11
	v_readlane_b32 s79, v243, 11
	v_cmp_gt_u64_e64 vcc, s[72:73], v[242:243]
	v_cmp_gt_u64_e64 s[0:1], s[74:75], v[242:243]
	v_cmp_gt_u64_e64 s[2:3], s[76:77], v[242:243]
	v_cmp_gt_u64_e64 s[4:5], s[78:79], v[242:243]
	v_addc_co_u32_e64 v249, vcc, 0, v249, vcc
	v_addc_co_u32_e64 v187, s[0:1], 0, v187, s[0:1]
	v_addc_co_u32_e64 v249, s[2:3], 0, v249, s[2:3]
	v_addc_co_u32_e64 v187, s[4:5], 0, v187, s[4:5]
	s_cmpk_le_u32 s82, 12
	s_cbranch_scc1 .Lsel_rank_done
	v_readlane_b32 s72, v242, 12
	v_readlane_b32 s73, v243, 12
	v_readlane_b32 s74, v242, 13
	v_readlane_b32 s75, v243, 13
	v_readlane_b32 s76, v242, 14
	v_readlane_b32 s77, v243, 14
	v_readlane_b32 s78, v242, 15
	v_readlane_b32 s79, v243, 15
	v_cmp_gt_u64_e64 vcc, s[72:73], v[242:243]
	v_cmp_gt_u64_e64 s[0:1], s[74:75], v[242:243]
	v_cmp_gt_u64_e64 s[2:3], s[76:77], v[242:243]
	v_cmp_gt_u64_e64 s[4:5], s[78:79], v[242:243]
	v_addc_co_u32_e64 v249, vcc, 0, v249, vcc
	v_addc_co_u32_e64 v187, s[0:1], 0, v187, s[0:1]
	v_addc_co_u32_e64 v249, s[2:3], 0, v249, s[2:3]
	v_addc_co_u32_e64 v187, s[4:5], 0, v187, s[4:5]
	s_cmpk_le_u32 s82, 16
	s_cbranch_scc1 .Lsel_rank_done
	v_readlane_b32 s72, v242, 16
	v_readlane_b32 s73, v243, 16
	v_readlane_b32 s74, v242, 17
	v_readlane_b32 s75, v243, 17
	v_readlane_b32 s76, v242, 18
	v_readlane_b32 s77, v243, 18
	v_readlane_b32 s78, v242, 19
	v_readlane_b32 s79, v243, 19
	v_cmp_gt_u64_e64 vcc, s[72:73], v[242:243]
	v_cmp_gt_u64_e64 s[0:1], s[74:75], v[242:243]
	v_cmp_gt_u64_e64 s[2:3], s[76:77], v[242:243]
	v_cmp_gt_u64_e64 s[4:5], s[78:79], v[242:243]
	v_addc_co_u32_e64 v249, vcc, 0, v249, vcc
	v_addc_co_u32_e64 v187, s[0:1], 0, v187, s[0:1]
	v_addc_co_u32_e64 v249, s[2:3], 0, v249, s[2:3]
	v_addc_co_u32_e64 v187, s[4:5], 0, v187, s[4:5]
	s_cmpk_le_u32 s82, 20
	s_cbranch_scc1 .Lsel_rank_done
	v_readlane_b32 s72, v242, 20
	v_readlane_b32 s73, v243, 20
	v_readlane_b32 s74, v242, 21
	v_readlane_b32 s75, v243, 21
	v_readlane_b32 s76, v242, 22
	v_readlane_b32 s77, v243, 22
	v_readlane_b32 s78, v242, 23
	v_readlane_b32 s79, v243, 23
	v_cmp_gt_u64_e64 vcc, s[72:73], v[242:243]
	v_cmp_gt_u64_e64 s[0:1], s[74:75], v[242:243]
	v_cmp_gt_u64_e64 s[2:3], s[76:77], v[242:243]
	v_cmp_gt_u64_e64 s[4:5], s[78:79], v[242:243]
	v_addc_co_u32_e64 v249, vcc, 0, v249, vcc
	v_addc_co_u32_e64 v187, s[0:1], 0, v187, s[0:1]
	v_addc_co_u32_e64 v249, s[2:3], 0, v249, s[2:3]
	v_addc_co_u32_e64 v187, s[4:5], 0, v187, s[4:5]
	s_cmpk_le_u32 s82, 24
	s_cbranch_scc1 .Lsel_rank_done
	v_readlane_b32 s72, v242, 24
	v_readlane_b32 s73, v243, 24
	v_readlane_b32 s74, v242, 25
	v_readlane_b32 s75, v243, 25
	v_readlane_b32 s76, v242, 26
	v_readlane_b32 s77, v243, 26
	v_readlane_b32 s78, v242, 27
	v_readlane_b32 s79, v243, 27
	v_cmp_gt_u64_e64 vcc, s[72:73], v[242:243]
	v_cmp_gt_u64_e64 s[0:1], s[74:75], v[242:243]
	v_cmp_gt_u64_e64 s[2:3], s[76:77], v[242:243]
	v_cmp_gt_u64_e64 s[4:5], s[78:79], v[242:243]
	v_addc_co_u32_e64 v249, vcc, 0, v249, vcc
	v_addc_co_u32_e64 v187, s[0:1], 0, v187, s[0:1]
	v_addc_co_u32_e64 v249, s[2:3], 0, v249, s[2:3]
	v_addc_co_u32_e64 v187, s[4:5], 0, v187, s[4:5]
	s_cmpk_le_u32 s82, 28
	s_cbranch_scc1 .Lsel_rank_done
	v_readlane_b32 s72, v242, 28
	v_readlane_b32 s73, v243, 28
	v_readlane_b32 s74, v242, 29
	v_readlane_b32 s75, v243, 29
	v_readlane_b32 s76, v242, 30
	v_readlane_b32 s77, v243, 30
	v_readlane_b32 s78, v242, 31
	v_readlane_b32 s79, v243, 31
	v_cmp_gt_u64_e64 vcc, s[72:73], v[242:243]
	v_cmp_gt_u64_e64 s[0:1], s[74:75], v[242:243]
	v_cmp_gt_u64_e64 s[2:3], s[76:77], v[242:243]
	v_cmp_gt_u64_e64 s[4:5], s[78:79], v[242:243]
	v_addc_co_u32_e64 v249, vcc, 0, v249, vcc
	v_addc_co_u32_e64 v187, s[0:1], 0, v187, s[0:1]
	v_addc_co_u32_e64 v249, s[2:3], 0, v249, s[2:3]
	v_addc_co_u32_e64 v187, s[4:5], 0, v187, s[4:5]
	s_cmpk_le_u32 s82, 32
	s_cbranch_scc1 .Lsel_rank_done
	v_readlane_b32 s72, v242, 32
	v_readlane_b32 s73, v243, 32
	v_readlane_b32 s74, v242, 33
	v_readlane_b32 s75, v243, 33
	v_readlane_b32 s76, v242, 34
	v_readlane_b32 s77, v243, 34
	v_readlane_b32 s78, v242, 35
	v_readlane_b32 s79, v243, 35
	v_cmp_gt_u64_e64 vcc, s[72:73], v[242:243]
	v_cmp_gt_u64_e64 s[0:1], s[74:75], v[242:243]
	v_cmp_gt_u64_e64 s[2:3], s[76:77], v[242:243]
	v_cmp_gt_u64_e64 s[4:5], s[78:79], v[242:243]
	v_addc_co_u32_e64 v249, vcc, 0, v249, vcc
	v_addc_co_u32_e64 v187, s[0:1], 0, v187, s[0:1]
	v_addc_co_u32_e64 v249, s[2:3], 0, v249, s[2:3]
	v_addc_co_u32_e64 v187, s[4:5], 0, v187, s[4:5]
	s_cmpk_le_u32 s82, 36
	s_cbranch_scc1 .Lsel_rank_done
	v_readlane_b32 s72, v242, 36
	v_readlane_b32 s73, v243, 36
	v_readlane_b32 s74, v242, 37
	v_readlane_b32 s75, v243, 37
	v_readlane_b32 s76, v242, 38
	v_readlane_b32 s77, v243, 38
	v_readlane_b32 s78, v242, 39
	v_readlane_b32 s79, v243, 39
	v_cmp_gt_u64_e64 vcc, s[72:73], v[242:243]
	v_cmp_gt_u64_e64 s[0:1], s[74:75], v[242:243]
	v_cmp_gt_u64_e64 s[2:3], s[76:77], v[242:243]
	v_cmp_gt_u64_e64 s[4:5], s[78:79], v[242:243]
	v_addc_co_u32_e64 v249, vcc, 0, v249, vcc
	v_addc_co_u32_e64 v187, s[0:1], 0, v187, s[0:1]
	v_addc_co_u32_e64 v249, s[2:3], 0, v249, s[2:3]
	v_addc_co_u32_e64 v187, s[4:5], 0, v187, s[4:5]
	s_cmpk_le_u32 s82, 40
	s_cbranch_scc1 .Lsel_rank_done
	v_readlane_b32 s72, v242, 40
	v_readlane_b32 s73, v243, 40
	v_readlane_b32 s74, v242, 41
	v_readlane_b32 s75, v243, 41
	v_readlane_b32 s76, v242, 42
	v_readlane_b32 s77, v243, 42
	v_readlane_b32 s78, v242, 43
	v_readlane_b32 s79, v243, 43
	v_cmp_gt_u64_e64 vcc, s[72:73], v[242:243]
	v_cmp_gt_u64_e64 s[0:1], s[74:75], v[242:243]
	v_cmp_gt_u64_e64 s[2:3], s[76:77], v[242:243]
	v_cmp_gt_u64_e64 s[4:5], s[78:79], v[242:243]
	v_addc_co_u32_e64 v249, vcc, 0, v249, vcc
	v_addc_co_u32_e64 v187, s[0:1], 0, v187, s[0:1]
	v_addc_co_u32_e64 v249, s[2:3], 0, v249, s[2:3]
	v_addc_co_u32_e64 v187, s[4:5], 0, v187, s[4:5]
	s_cmpk_le_u32 s82, 44
	s_cbranch_scc1 .Lsel_rank_done
	v_readlane_b32 s72, v242, 44
	v_readlane_b32 s73, v243, 44
	v_readlane_b32 s74, v242, 45
	v_readlane_b32 s75, v243, 45
	v_readlane_b32 s76, v242, 46
	v_readlane_b32 s77, v243, 46
	v_readlane_b32 s78, v242, 47
	v_readlane_b32 s79, v243, 47
	v_cmp_gt_u64_e64 vcc, s[72:73], v[242:243]
	v_cmp_gt_u64_e64 s[0:1], s[74:75], v[242:243]
	v_cmp_gt_u64_e64 s[2:3], s[76:77], v[242:243]
	v_cmp_gt_u64_e64 s[4:5], s[78:79], v[242:243]
	v_addc_co_u32_e64 v249, vcc, 0, v249, vcc
	v_addc_co_u32_e64 v187, s[0:1], 0, v187, s[0:1]
	v_addc_co_u32_e64 v249, s[2:3], 0, v249, s[2:3]
	v_addc_co_u32_e64 v187, s[4:5], 0, v187, s[4:5]
	s_cmpk_le_u32 s82, 48
	s_cbranch_scc1 .Lsel_rank_done
	v_readlane_b32 s72, v242, 48
	v_readlane_b32 s73, v243, 48
	v_readlane_b32 s74, v242, 49
	v_readlane_b32 s75, v243, 49
	v_readlane_b32 s76, v242, 50
	v_readlane_b32 s77, v243, 50
	v_readlane_b32 s78, v242, 51
	v_readlane_b32 s79, v243, 51
	v_cmp_gt_u64_e64 vcc, s[72:73], v[242:243]
	v_cmp_gt_u64_e64 s[0:1], s[74:75], v[242:243]
	v_cmp_gt_u64_e64 s[2:3], s[76:77], v[242:243]
	v_cmp_gt_u64_e64 s[4:5], s[78:79], v[242:243]
	v_addc_co_u32_e64 v249, vcc, 0, v249, vcc
	v_addc_co_u32_e64 v187, s[0:1], 0, v187, s[0:1]
	v_addc_co_u32_e64 v249, s[2:3], 0, v249, s[2:3]
	v_addc_co_u32_e64 v187, s[4:5], 0, v187, s[4:5]
	s_cmpk_le_u32 s82, 52
	s_cbranch_scc1 .Lsel_rank_done
	v_readlane_b32 s72, v242, 52
	v_readlane_b32 s73, v243, 52
	v_readlane_b32 s74, v242, 53
	v_readlane_b32 s75, v243, 53
	v_readlane_b32 s76, v242, 54
	v_readlane_b32 s77, v243, 54
	v_readlane_b32 s78, v242, 55
	v_readlane_b32 s79, v243, 55
	v_cmp_gt_u64_e64 vcc, s[72:73], v[242:243]
	v_cmp_gt_u64_e64 s[0:1], s[74:75], v[242:243]
	v_cmp_gt_u64_e64 s[2:3], s[76:77], v[242:243]
	v_cmp_gt_u64_e64 s[4:5], s[78:79], v[242:243]
	v_addc_co_u32_e64 v249, vcc, 0, v249, vcc
	v_addc_co_u32_e64 v187, s[0:1], 0, v187, s[0:1]
	v_addc_co_u32_e64 v249, s[2:3], 0, v249, s[2:3]
	v_addc_co_u32_e64 v187, s[4:5], 0, v187, s[4:5]
	s_cmpk_le_u32 s82, 56
	s_cbranch_scc1 .Lsel_rank_done
	v_readlane_b32 s72, v242, 56
	v_readlane_b32 s73, v243, 56
	v_readlane_b32 s74, v242, 57
	v_readlane_b32 s75, v243, 57
	v_readlane_b32 s76, v242, 58
	v_readlane_b32 s77, v243, 58
	v_readlane_b32 s78, v242, 59
	v_readlane_b32 s79, v243, 59
	v_cmp_gt_u64_e64 vcc, s[72:73], v[242:243]
	v_cmp_gt_u64_e64 s[0:1], s[74:75], v[242:243]
	v_cmp_gt_u64_e64 s[2:3], s[76:77], v[242:243]
	v_cmp_gt_u64_e64 s[4:5], s[78:79], v[242:243]
	v_addc_co_u32_e64 v249, vcc, 0, v249, vcc
	v_addc_co_u32_e64 v187, s[0:1], 0, v187, s[0:1]
	v_addc_co_u32_e64 v249, s[2:3], 0, v249, s[2:3]
	v_addc_co_u32_e64 v187, s[4:5], 0, v187, s[4:5]
	s_cmpk_le_u32 s82, 60
	s_cbranch_scc1 .Lsel_rank_done
	v_readlane_b32 s72, v242, 60
	v_readlane_b32 s73, v243, 60
	v_readlane_b32 s74, v242, 61
	v_readlane_b32 s75, v243, 61
	v_readlane_b32 s76, v242, 62
	v_readlane_b32 s77, v243, 62
	v_readlane_b32 s78, v242, 63
	v_readlane_b32 s79, v243, 63
	v_cmp_gt_u64_e64 vcc, s[72:73], v[242:243]
	v_cmp_gt_u64_e64 s[0:1], s[74:75], v[242:243]
	v_cmp_gt_u64_e64 s[2:3], s[76:77], v[242:243]
	v_cmp_gt_u64_e64 s[4:5], s[78:79], v[242:243]
	v_addc_co_u32_e64 v249, vcc, 0, v249, vcc
	v_addc_co_u32_e64 v187, s[0:1], 0, v187, s[0:1]
	v_addc_co_u32_e64 v249, s[2:3], 0, v249, s[2:3]
	v_addc_co_u32_e64 v187, s[4:5], 0, v187, s[4:5]
.Lsel_rank_done:
	v_add_u32_e32 v249, v249, v187
	v_cmp_gt_u32_e32 vcc, s81, v249
	v_cmp_gt_u32_e64 s[0:1], s82, v198
	v_and_b32_e32 v193, 4, v248
	v_lshlrev_b32_e32 v193, 3, v193
	v_lshrrev_b32_e32 v187, 8, v248
	v_lshl_add_u32 v193, v187, 2, v193
	v_bfe_u32 v194, v248, 6, 2
	v_add_u32_e32 v193, v193, v194
	s_and_b32 s7, s28, 7
	s_lshl_b32 s7, s7, 8
	s_add_i32 s7, s7, 0xc000
	s_nop 1
	v_lshl_add_u32 v193, v193, 2, s7
	v_bfe_u32 v194, v248, 3, 3
	v_and_b32_e32 v192, 3, v248
	v_lshl_add_u32 v194, v194, 2, v192
	v_lshlrev_b32_e32 v194, v194, v233
	s_and_b64 s[0:1], s[0:1], vcc
	s_mov_b64 exec, s[0:1]
	ds_or_b32 v193, v194
	s_mov_b64 exec, -1
.Lsel_E:
	v_mov_b32_e32 v195, 0
	v_mov_b32_e32 v196, s80
	s_cmpk_lt_u32 s6, 7
	s_cbranch_scc1 .Lsel_E_6
	v_sub_u32_e32 v193, v196, v230
	v_sub_u32_e32 v192, v196, v229
	v_sub_u32_e32 v187, v196, v228
	v_sub_u32_e32 v186, v196, v227
	v_alignbit_b32 v195, v195, v193, 31
	v_alignbit_b32 v195, v195, v192, 31
	v_alignbit_b32 v195, v195, v187, 31
	v_alignbit_b32 v195, v195, v186, 31
.Lsel_E_6:
	s_cmpk_lt_u32 s6, 6
	s_cbranch_scc1 .Lsel_E_5
	v_sub_u32_e32 v193, v196, v226
	v_sub_u32_e32 v192, v196, v225
	v_sub_u32_e32 v187, v196, v224
	v_sub_u32_e32 v186, v196, v223
	v_alignbit_b32 v195, v195, v193, 31
	v_alignbit_b32 v195, v195, v192, 31
	v_alignbit_b32 v195, v195, v187, 31
	v_alignbit_b32 v195, v195, v186, 31
.Lsel_E_5:
	s_cmpk_lt_u32 s6, 5
	s_cbranch_scc1 .Lsel_E_4
	v_sub_u32_e32 v193, v196, v222
	v_sub_u32_e32 v192, v196, v221
	v_sub_u32_e32 v187, v196, v220
	v_sub_u32_e32 v186, v196, v219
	v_alignbit_b32 v195, v195, v193, 31
	v_alignbit_b32 v195, v195, v192, 31
	v_alignbit_b32 v195, v195, v187, 31
	v_alignbit_b32 v195, v195, v186, 31
.Lsel_E_4:
	s_cmpk_lt_u32 s6, 4
	s_cbranch_scc1 .Lsel_E_3
	v_sub_u32_e32 v193, v196, v218
	v_sub_u32_e32 v192, v196, v217
	v_sub_u32_e32 v187, v196, v216
	v_sub_u32_e32 v186, v196, v215
	v_alignbit_b32 v195, v195, v193, 31
	v_alignbit_b32 v195, v195, v192, 31
	v_alignbit_b32 v195, v195, v187, 31
	v_alignbit_b32 v195, v195, v186, 31
.Lsel_E_3:
	s_cmpk_lt_u32 s6, 3
	s_cbranch_scc1 .Lsel_E_2
	v_sub_u32_e32 v193, v196, v214
	v_sub_u32_e32 v192, v196, v213
	v_sub_u32_e32 v187, v196, v212
	v_sub_u32_e32 v186, v196, v211
	v_alignbit_b32 v195, v195, v193, 31
	v_alignbit_b32 v195, v195, v192, 31
	v_alignbit_b32 v195, v195, v187, 31
	v_alignbit_b32 v195, v195, v186, 31
.Lsel_E_2:
	s_cmpk_lt_u32 s6, 2
	s_cbranch_scc1 .Lsel_E_1
	v_sub_u32_e32 v193, v196, v210
	v_sub_u32_e32 v192, v196, v209
	v_sub_u32_e32 v187, v196, v208
	v_sub_u32_e32 v186, v196, v207
	v_alignbit_b32 v195, v195, v193, 31
	v_alignbit_b32 v195, v195, v192, 31
	v_alignbit_b32 v195, v195, v187, 31
	v_alignbit_b32 v195, v195, v186, 31
.Lsel_E_1:
	v_sub_u32_e32 v193, v196, v206
	v_sub_u32_e32 v192, v196, v205
	v_sub_u32_e32 v187, v196, v204
	v_sub_u32_e32 v186, v196, v203
	v_alignbit_b32 v195, v195, v193, 31
	v_alignbit_b32 v195, v195, v192, 31
	v_alignbit_b32 v195, v195, v187, 31
	v_alignbit_b32 v195, v195, v186, 31
.Lsel_E_0:
	v_sub_u32_e32 v193, v196, v202
	v_sub_u32_e32 v192, v196, v201
	v_sub_u32_e32 v187, v196, v200
	v_sub_u32_e32 v186, v196, v199
	v_alignbit_b32 v195, v195, v193, 31
	v_alignbit_b32 v195, v195, v192, 31
	v_alignbit_b32 v195, v195, v187, 31
	v_alignbit_b32 v195, v195, v186, 31
	s_and_b32 s7, s28, 7
	s_lshl_b32 s7, s7, 8
	s_add_i32 s7, s7, 0xc000
	v_and_b32_e32 v186, 1, v198
	v_lshlrev_b32_e32 v186, 7, v186
	v_lshrrev_b32_e32 v187, 4, v198
	v_lshl_add_u32 v186, v187, 2, v186
	v_add_u32_e32 v186, s7, v186
	v_lshlrev_b32_e32 v187, 1, v198
	v_and_b32_e32 v187, 28, v187
	v_bfe_u32 v192, v195, 0, 4
	v_lshlrev_b32_e32 v192, v187, v192
	ds_or_b32 v186, v192
	v_bfe_u32 v193, v195, 4, 4
	v_lshlrev_b32_e32 v193, v187, v193
	ds_or_b32 v186, v193 offset:16
	v_bfe_u32 v240, v195, 8, 4
	v_lshlrev_b32_e32 v240, v187, v240
	ds_or_b32 v186, v240 offset:32
	v_bfe_u32 v241, v195, 12, 4
	v_lshlrev_b32_e32 v241, v187, v241
	ds_or_b32 v186, v241 offset:48
	v_bfe_u32 v192, v195, 16, 4
	v_lshlrev_b32_e32 v192, v187, v192
	ds_or_b32 v186, v192 offset:64
	v_bfe_u32 v193, v195, 20, 4
	v_lshlrev_b32_e32 v193, v187, v193
	ds_or_b32 v186, v193 offset:80
	v_bfe_u32 v240, v195, 24, 4
	v_lshlrev_b32_e32 v240, v187, v240
	ds_or_b32 v186, v240 offset:96
	v_bfe_u32 v241, v195, 28, 4
	v_lshlrev_b32_e32 v241, v187, v241
	ds_or_b32 v186, v241 offset:112
	s_waitcnt lgkmcnt(0)
	ds_read_b32 v1, v237
	v_add_u32_e32 v74, s28, v159
	v_lshl_add_u64 v[2:3], v[74:75], 2, s[20:21]
	s_waitcnt lgkmcnt(0)
	global_store_dword v[2:3], v1, off
	s_add_i32 s0, s28, 8
	s_cmp_lt_u32 s28, 24
	s_mov_b32 s28, s0
	s_cbranch_scc0 .LBB0_699
	s_branch .LBB0_721
.Lsel_bail:
	s_mov_b64 exec, -1
	s_waitcnt vmcnt(0) lgkmcnt(0)
